# grid barrier release side shortened: every workgroup polls the cross-XCD arrival counter directly (no TOPGEN/XGEN relay hops); same write-back and invalidates
# speedup vs baseline: 1.0146x; 1.0146x over previous
; __device__ __forceinline__ unsigned xb_ld(unsigned* p)              { return __hip_atomic_load(p, __ATOMIC_RELAXED, __HIP_MEMORY_SCOPE_AGENT); }
; __device__ __forceinline__ unsigned xb_add(unsigned* p, unsigned v) { return __hip_atomic_fetch_add(p, v, __ATOMIC_RELAXED, __HIP_MEMORY_SCOPE_AGENT); }
; #define XB_SPIN(cond, bar) do { unsigned _sp = 0; while (cond) { __builtin_amdgcn_s_sleep(1); \
;     if ((++_sp & 255u) == 0u) { if (xb_ld(&(bar)[XB_TMO])) break; if (_sp > XB_SPIN_CAP) { atomicAdd(&(bar)[XB_TMO], 1u); break; } } } } while (0)
; __device__ __forceinline__ void xcd_barrier(const XcdBarrier& b) {
;     asm volatile("s_waitcnt vmcnt(0)" ::: "memory");
;     __syncthreads();
;     if (threadIdx.x == 0) {
;         unsigned* bar = b.bar;
;         __builtin_amdgcn_s_waitcnt(0);
;         unsigned nloc = b.st[0], nx = b.st[1];
;         if (nloc == 0u) { xcd_barrier_complete(bar, b.x, nloc, nx); b.st[0] = nloc; b.st[1] = nx; }
;         const unsigned old = xb_add(&bar[XB_XSUB(b.x)], 1u);
;         const unsigned gen = old / nloc;
;         if (old + 1u == (gen + 1u) * nloc) {
;             __builtin_amdgcn_fence(__ATOMIC_RELEASE, "agent");
;             asm volatile("s_waitcnt vmcnt(0)" ::: "memory");
;             const unsigned og = xb_add(&bar[XB_TOP], 1u);
;             const unsigned tg = og / nx;
;             if (og + 1u == (tg + 1u) * nx) xb_add(&bar[XB_TOPGEN], 1u);
;             else XB_SPIN(xb_ld(&bar[XB_TOPGEN]) == tg, bar);
;             __builtin_amdgcn_fence(__ATOMIC_ACQUIRE, "agent");
;             xb_add(&bar[XB_XGEN(b.x)], 1u);
;             asm volatile("s_waitcnt vmcnt(0)" ::: "memory");
;         } else {
;             XB_SPIN(xb_ld(&bar[XB_XGEN(b.x)]) == gen, bar);
;             __builtin_amdgcn_fence(__ATOMIC_ACQUIRE, "agent");
;             asm volatile("s_waitcnt vmcnt(0)" ::: "memory");
;         }
;     }
;     __syncthreads();
; }
.LBB0_140:
	s_waitcnt lgkmcnt(0)
	v_readfirstlane_b32 s98, v2
	v_readfirstlane_b32 s99, v0
	v_mov_b32_e32 v1, 0x20008
	ds_read_b32 v5, v1
	s_lshl_b32 s96, s59, 8
	s_add_u32 s96, s54, s96
	s_addc_u32 s97, s55, 0
	v_mov_b32_e32 v3, 0x1000
	v_mov_b32_e32 v4, 1
	global_atomic_add v3, v3, v4, s[96:97] offset:1024 sc0
	s_waitcnt lgkmcnt(0)
	v_readfirstlane_b32 s100, v5
	s_add_i32 s100, s100, 1
	v_mov_b32_e32 v2, s100
	ds_write_b32 v1, v2
	s_mul_i32 s98, s98, s100
	s_mul_i32 s99, s99, s100
	s_waitcnt vmcnt(0)
	v_readfirstlane_b32 s96, v3
	s_add_i32 s96, s96, 1
	s_cmp_lg_u32 s96, s98
	s_cbranch_scc1 .Lmy_bar_poll_0
	buffer_wbl2 sc1
	s_waitcnt vmcnt(0)
	v_mov_b32_e32 v3, 0x3000
	global_atomic_add v3, v4, s[54:55] offset:1024
.Lmy_bar_poll_0:
	v_mov_b32_e32 v3, 0x3000
	s_mov_b32 s97, 0
.Lmy_bar_spin_0:
	global_load_dword v4, v3, s[54:55] offset:1024 sc1
	s_waitcnt vmcnt(0)
	v_readfirstlane_b32 s96, v4
	s_sub_i32 s96, s96, s99
	s_cmp_ge_i32 s96, 0
	s_cbranch_scc1 .Lmy_bar_go_0
	s_sleep 1
	s_add_i32 s97, s97, 1
	s_cmp_lt_u32 s97, 0x40000
	s_cbranch_scc1 .Lmy_bar_spin_0
.Lmy_bar_go_0:
	buffer_inv sc1
	s_waitcnt vmcnt(0)
